# flag-form group barriers; the original grid barrier stays as the path taken when the placement census is not one batch class per XCD
# baseline (speedup 1.0000x reference)
;     __host__ __device__ bool next(int i, Unit& u) const {
;         const long L = (long)i * G + c; if (L >= nwg) return false;
;         int wgid = (int)L; { const int q = nwg / NXCD, r = nwg % NXCD, xcd = wgid % NXCD, off = wgid / NXCD; wgid = (xcd < r ? xcd * (q + 1) : r * (q + 1) + (xcd - r) * q) + off; }
;         const int nig = wgm * nN, gid = wgid / nig, fm = gid * wgm, gsz = (nM - fm) < wgm ? (nM - fm) : wgm;
;         u.pm = fm + ((wgid % nig) % gsz); u.pn = (wgid % nig) / gsz; return true;
; template <class Epi, class Sched, bool ALIGN_EPI = false, bool SP2 = false>
; __device__ __forceinline__ void gemm_phase(PG8_LAS unsigned char* lds, const Gemm g, const Sched& S, const Epi& E) {
;     ...
;     if (!S.next(0, cur)) return;
.LBB0_181:
	s_or_b64 exec, exec, s[0:1]
	v_mov_b32_e32 v10, v0
	s_cmpk_lt_i32 s96, 0x4c0
	s_waitcnt lgkmcnt(0)
	s_barrier
	s_cselect_b32 s100, 1, 0
	v_and_b32_e32 v1, 63, v0
	v_lshlrev_b32_e32 v1, 2, v1
	v_add_u32_e32 v1, 0x41000, v1
	global_load_dword v2, v1, s[88:89] sc1
	global_load_dword v3, v1, s[88:89] offset:256 sc1
	s_waitcnt vmcnt(0)
	v_cmp_eq_u32_e32 vcc, 32, v2
	s_bcnt1_i32_b64 s101, vcc
	v_cmp_eq_u32_e32 vcc, 32, v3
	s_bcnt1_i32_b64 vcc_lo, vcc
	s_add_i32 s101, s101, vcc_lo
	s_cmp_lg_u32 s101, 8
	s_cselect_b32 s101, 1, 0
	s_or_b32 s98, s98, s101
	s_cmp_eq_u32 s100, 1
	s_cselect_b64 s[0:1], -1, 0
	s_cmpk_gt_i32 s96, 0x4bf
	v_readfirstlane_b32 s2, v10
	s_cbranch_scc1 .LBB0_183
	s_ashr_i32 s3, s96, 31
	s_lshr_b32 s3, s3, 29
	s_add_i32 s3, s96, s3
	s_ashr_i32 s4, s3, 3
	s_and_b32 s3, s3, -8
	s_sub_i32 s3, s96, s3
	s_cmp_lt_i32 s3, 0
	s_movk_i32 s5, 0x99
	s_cselect_b32 s5, s5, 0x98
	s_mul_i32 s3, s5, s3
	s_add_i32 s3, s3, s4
	s_mul_hi_i32 s4, s3, 0x6bca1af3
	s_lshr_b32 s5, s4, 31
	s_ashr_i32 s4, s4, 4
	s_add_i32 s4, s4, s5
	s_lshl_b32 s5, s4, 1
	s_mul_i32 s4, s4, 38
	s_sub_i32 s3, s3, s4
	s_bfe_u32 s4, s3, 0x10007
	s_add_i32 s4, s3, s4
	s_bfe_i32 s6, s4, 0x80000
	s_and_b32 s4, s4, 0xfe
	s_sub_i32 s3, s3, s4
	s_sext_i32_i16 s6, s6
	s_sext_i32_i8 s3, s3
	s_add_i32 s18, s5, s3
	s_ashr_i32 s4, s6, 1

; __device__ __forceinline__ unsigned xb_ld(unsigned* p)              { return __hip_atomic_load(p, __ATOMIC_RELAXED, __HIP_MEMORY_SCOPE_AGENT); }
; __device__ __forceinline__ unsigned xb_add(unsigned* p, unsigned v) { return __hip_atomic_fetch_add(p, v, __ATOMIC_RELAXED, __HIP_MEMORY_SCOPE_AGENT); }
; #define XB_SPIN(cond, bar) do { unsigned _sp = 0; while (cond) { __builtin_amdgcn_s_sleep(1); \
;     if ((++_sp & 255u) == 0u) { if (xb_ld(&(bar)[XB_TMO])) break; if (_sp > XB_SPIN_CAP) { atomicAdd(&(bar)[XB_TMO], 1u); break; } } } } while (0)
; __device__ __forceinline__ void xcd_barrier(const XcdBarrier& b) {
;     asm volatile("s_waitcnt vmcnt(0)" ::: "memory");
;     __syncthreads();
;     if (threadIdx.x == 0) {
;         unsigned* bar = b.bar;
;         __builtin_amdgcn_s_waitcnt(0);
;         unsigned nloc = b.st[0], nx = b.st[1];
;         if (nloc == 0u) { xcd_barrier_complete(bar, b.x, nloc, nx); b.st[0] = nloc; b.st[1] = nx; }
;         const unsigned old = xb_add(&bar[XB_XSUB(b.x)], 1u);
;         const unsigned gen = old / nloc;
;         asm volatile("buffer_inv sc1" ::: "memory");
;         if (old + 1u == (gen + 1u) * nloc) {
;             __builtin_amdgcn_fence(__ATOMIC_RELEASE, "agent");
;             asm volatile("s_waitcnt vmcnt(0)" ::: "memory");
;             const unsigned og = xb_add(&bar[XB_TOP], 1u);
;             const unsigned tg = og / nx;
;             if (og + 1u == (tg + 1u) * nx) xb_add(&bar[XB_TOPGEN], 1u);
;             else XB_SPIN(xb_ld(&bar[XB_TOPGEN]) == tg, bar);
;             asm volatile("" ::: "memory");
;             xb_add(&bar[XB_XGEN(b.x)], 1u);
;             asm volatile("s_waitcnt vmcnt(0)" ::: "memory");
;         } else {
;             XB_SPIN(xb_ld(&bar[XB_XGEN(b.x)]) == gen, bar);
;             asm volatile("" ::: "memory");
;             asm volatile("s_waitcnt vmcnt(0)" ::: "memory");
;         }
;     }
;     __syncthreads();
.LBB0_233:
	s_waitcnt vmcnt(0)
	s_waitcnt vmcnt(0)
	s_barrier
	s_mov_b64 s[0:1], exec
	v_readlane_b32 s2, v241, 34
	v_readlane_b32 s3, v241, 35
	s_and_b64 s[2:3], s[0:1], s[2:3]
	v_writelane_b32 v241, s94, 55
	s_nop 1
	v_writelane_b32 v241, s95, 56
	s_mov_b64 exec, s[2:3]
	s_cbranch_execz .LBB0_289
	s_bitcmp1_b32 s98, 0
	s_cbranch_scc1 .Lgb_orig1
	s_waitcnt vmcnt(0) lgkmcnt(0)
	s_and_b32 s100, s98, -4
	v_mov_b32_e32 v1, s100
	v_mov_b32_e32 v2, 1
	global_store_dword v1, v2, s[88:89] offset:1024
	buffer_inv sc1
	s_mov_b32 exec_lo, -1
	s_mov_b32 exec_hi, 0
	v_mbcnt_lo_u32_b32 v3, -1, 0
	v_lshl_add_u32 v3, v3, 2, s99
	s_mov_b32 s100, 0

; __device__ __forceinline__ unsigned xb_ld(unsigned* p)              { return __hip_atomic_load(p, __ATOMIC_RELAXED, __HIP_MEMORY_SCOPE_AGENT); }
; __device__ __forceinline__ unsigned xb_add(unsigned* p, unsigned v) { return __hip_atomic_fetch_add(p, v, __ATOMIC_RELAXED, __HIP_MEMORY_SCOPE_AGENT); }
; __device__ __forceinline__ void xcd_barrier_complete(unsigned* bar, unsigned x, unsigned& nloc, unsigned& nx) {
;     const unsigned G = gridDim.x * gridDim.y * gridDim.z;
;     unsigned sum, cnt, mine, sp = 0u;
;     for (;;) {
;         sum = 0u; cnt = 0u; mine = 0u;
; #pragma unroll
;         for (unsigned j = 0; j < 16; ++j) { const unsigned c = xb_ld(&bar[XB_XCNT(j)]); sum += c; cnt += (c > 0u) ? 1u : 0u; mine = (j == x) ? c : mine; }
;         if (sum == G) break;
;         __builtin_amdgcn_s_sleep(1);
;         if ((++sp & 255u) == 0u) { if (xb_ld(&bar[XB_TMO])) break; if (sp > XB_SPIN_CAP) { atomicAdd(&bar[XB_TMO], 1u); break; } }
;     }
;     nloc = mine > 0u ? mine : 1u; nx = cnt > 0u ? cnt : 1u;
; }
; __device__ __forceinline__ void xcd_barrier(const XcdBarrier& b) {
;     asm volatile("s_waitcnt vmcnt(0)" ::: "memory");
;     __syncthreads();
;     if (threadIdx.x == 0) {
;         unsigned* bar = b.bar;
;         __builtin_amdgcn_s_waitcnt(0);
;         unsigned nloc = b.st[0], nx = b.st[1];
;         if (nloc == 0u) { xcd_barrier_complete(bar, b.x, nloc, nx); b.st[0] = nloc; b.st[1] = nx; }
;         const unsigned old = xb_add(&bar[XB_XSUB(b.x)], 1u);
.Lgb_orig1:
	s_add_i32 s2, 0, 0x27f60
	v_mov_b32_e32 v1, s2
	s_waitcnt vmcnt(0) expcnt(0) lgkmcnt(0)
	ds_read_b32 v3, v1
	s_add_i32 s2, 0, 0x27f64
	v_mov_b32_e32 v1, s2
	ds_read_b32 v1, v1
	s_waitcnt lgkmcnt(1)
	v_cmp_ne_u32_e32 vcc, 0, v3
	s_cbranch_vccnz .LBB0_252
	v_readlane_b32 s2, v241, 0
	v_readlane_b32 s3, v241, 1
	s_load_dwordx2 s[6:7], s[2:3], 0x4
	s_add_u32 s2, s88, 0x4200
	s_addc_u32 s3, s89, 0
	s_add_u32 s4, s88, 0x4400
	s_addc_u32 s5, s89, 0
	s_waitcnt lgkmcnt(0)
	s_mul_i32 s30, s6, s93
	s_add_u32 s6, s88, 0x4500
	s_mul_i32 s30, s30, s7
	s_addc_u32 s7, s89, 0
	s_add_u32 s8, s88, 0x4600
	s_addc_u32 s9, s89, 0
	s_add_u32 s10, s88, 0x4700
	s_addc_u32 s11, s89, 0
	s_add_u32 s12, s88, 0x4800
	s_addc_u32 s13, s89, 0
	s_add_u32 s14, s88, 0x4900
	s_addc_u32 s15, s89, 0
	s_add_u32 s16, s88, 0x4a00
	s_addc_u32 s17, s89, 0
	s_add_u32 s18, s88, 0x4b00
	s_addc_u32 s19, s89, 0
	s_add_u32 s20, s88, 0x4c00
	s_addc_u32 s21, s89, 0
	s_add_u32 s22, s88, 0x4d00
	s_addc_u32 s23, s89, 0
	s_add_u32 s24, s88, 0x4e00
	s_addc_u32 s25, s89, 0
	s_add_u32 s26, s88, 0x4f00
	s_addc_u32 s27, s89, 0
	s_add_u32 s28, s88, 0x5000
	s_addc_u32 s29, s89, 0
	s_add_u32 s34, s88, 0x5100
	s_addc_u32 s35, s89, 0
	s_add_u32 s74, s88, 0x5200
	s_addc_u32 s75, s89, 0
	s_add_u32 s84, s88, 0x5300
	s_mov_b64 s[36:37], s[86:87]
	s_addc_u32 s85, s89, 0
	s_mov_b32 s31, 1
	v_mov_b32_e32 v17, 0
	s_branch .LBB0_237

; __device__ __forceinline__ unsigned xb_ld(unsigned* p)              { return __hip_atomic_load(p, __ATOMIC_RELAXED, __HIP_MEMORY_SCOPE_AGENT); }
; __device__ __forceinline__ unsigned xb_add(unsigned* p, unsigned v) { return __hip_atomic_fetch_add(p, v, __ATOMIC_RELAXED, __HIP_MEMORY_SCOPE_AGENT); }
; #define XB_SPIN(cond, bar) do { unsigned _sp = 0; while (cond) { __builtin_amdgcn_s_sleep(1); \
;     if ((++_sp & 255u) == 0u) { if (xb_ld(&(bar)[XB_TMO])) break; if (_sp > XB_SPIN_CAP) { atomicAdd(&(bar)[XB_TMO], 1u); break; } } } } while (0)
; __device__ __forceinline__ void xcd_barrier(const XcdBarrier& b) {
;     asm volatile("s_waitcnt vmcnt(0)" ::: "memory");
;     __syncthreads();
;     if (threadIdx.x == 0) {
;         unsigned* bar = b.bar;
;         __builtin_amdgcn_s_waitcnt(0);
;         unsigned nloc = b.st[0], nx = b.st[1];
;         if (nloc == 0u) { xcd_barrier_complete(bar, b.x, nloc, nx); b.st[0] = nloc; b.st[1] = nx; }
;         const unsigned old = xb_add(&bar[XB_XSUB(b.x)], 1u);
;         const unsigned gen = old / nloc;
;         asm volatile("buffer_inv sc1" ::: "memory");
;         if (old + 1u == (gen + 1u) * nloc) {
;             __builtin_amdgcn_fence(__ATOMIC_RELEASE, "agent");
;             asm volatile("s_waitcnt vmcnt(0)" ::: "memory");
;             const unsigned og = xb_add(&bar[XB_TOP], 1u);
;             const unsigned tg = og / nx;
;             if (og + 1u == (tg + 1u) * nx) xb_add(&bar[XB_TOPGEN], 1u);
;             else XB_SPIN(xb_ld(&bar[XB_TOPGEN]) == tg, bar);
;             asm volatile("" ::: "memory");
;             xb_add(&bar[XB_XGEN(b.x)], 1u);
;             asm volatile("s_waitcnt vmcnt(0)" ::: "memory");
;         } else {
;             XB_SPIN(xb_ld(&bar[XB_XGEN(b.x)]) == gen, bar);
;             asm volatile("" ::: "memory");
;             asm volatile("s_waitcnt vmcnt(0)" ::: "memory");
;         }
;     }
;     __syncthreads();
.LBB0_309:
	s_waitcnt vmcnt(0)
	s_barrier
	s_mov_b64 s[2:3], exec
	v_readlane_b32 s4, v241, 34
	v_readlane_b32 s5, v241, 35
	s_and_b64 s[4:5], s[2:3], s[4:5]
	s_mov_b64 exec, s[4:5]
	s_cbranch_execz .LBB0_361
	s_bitcmp1_b32 s98, 0
	s_cbranch_scc1 .Lgb_orig2
	s_waitcnt vmcnt(0) lgkmcnt(0)
	s_and_b32 s100, s98, -4
	v_mov_b32_e32 v1, s100
	v_mov_b32_e32 v2, 1
	global_store_dword v1, v2, s[88:89] offset:2048
	buffer_inv sc1
	s_mov_b32 exec_lo, -1
	s_mov_b32 exec_hi, 0
	v_mbcnt_lo_u32_b32 v3, -1, 0
	v_lshl_add_u32 v3, v3, 2, s99
	s_mov_b32 s100, 0

; __device__ __forceinline__ unsigned xb_ld(unsigned* p)              { return __hip_atomic_load(p, __ATOMIC_RELAXED, __HIP_MEMORY_SCOPE_AGENT); }
; __device__ __forceinline__ unsigned xb_add(unsigned* p, unsigned v) { return __hip_atomic_fetch_add(p, v, __ATOMIC_RELAXED, __HIP_MEMORY_SCOPE_AGENT); }
; __device__ __forceinline__ void xcd_barrier_complete(unsigned* bar, unsigned x, unsigned& nloc, unsigned& nx) {
;     const unsigned G = gridDim.x * gridDim.y * gridDim.z;
;     unsigned sum, cnt, mine, sp = 0u;
;     for (;;) {
;         sum = 0u; cnt = 0u; mine = 0u;
; #pragma unroll
;         for (unsigned j = 0; j < 16; ++j) { const unsigned c = xb_ld(&bar[XB_XCNT(j)]); sum += c; cnt += (c > 0u) ? 1u : 0u; mine = (j == x) ? c : mine; }
;         if (sum == G) break;
;         __builtin_amdgcn_s_sleep(1);
;         if ((++sp & 255u) == 0u) { if (xb_ld(&bar[XB_TMO])) break; if (sp > XB_SPIN_CAP) { atomicAdd(&bar[XB_TMO], 1u); break; } }
;     }
;     nloc = mine > 0u ? mine : 1u; nx = cnt > 0u ? cnt : 1u;
; }
; __device__ __forceinline__ void xcd_barrier(const XcdBarrier& b) {
;     asm volatile("s_waitcnt vmcnt(0)" ::: "memory");
;     __syncthreads();
;     if (threadIdx.x == 0) {
;         unsigned* bar = b.bar;
;         __builtin_amdgcn_s_waitcnt(0);
;         unsigned nloc = b.st[0], nx = b.st[1];
;         if (nloc == 0u) { xcd_barrier_complete(bar, b.x, nloc, nx); b.st[0] = nloc; b.st[1] = nx; }
;         const unsigned old = xb_add(&bar[XB_XSUB(b.x)], 1u);
.Lgb_orig2:
	s_add_i32 s4, 0, 0x27f60
	v_mov_b32_e32 v1, s4
	s_waitcnt vmcnt(0) expcnt(0) lgkmcnt(0)
	ds_read_b32 v3, v1
	s_add_i32 s4, 0, 0x27f64
	v_mov_b32_e32 v1, s4
	ds_read_b32 v1, v1
	s_waitcnt lgkmcnt(1)
	v_cmp_ne_u32_e32 vcc, 0, v3
	s_cbranch_vccnz .LBB0_325
	v_readlane_b32 s4, v241, 0
	v_readlane_b32 s5, v241, 1
	s_load_dwordx2 s[8:9], s[4:5], 0x4
	s_add_u32 s4, s88, 0x4200
	s_addc_u32 s5, s89, 0
	s_add_u32 s6, s88, 0x4400
	s_addc_u32 s7, s89, 0
	s_waitcnt lgkmcnt(0)
	s_mul_i32 s30, s8, s93
	s_add_u32 s8, s88, 0x4500
	s_mul_i32 s30, s30, s9
	s_addc_u32 s9, s89, 0
	s_add_u32 s10, s88, 0x4600
	s_addc_u32 s11, s89, 0
	s_add_u32 s14, s88, 0x4700
	s_addc_u32 s15, s89, 0
	s_add_u32 s16, s88, 0x4800
	s_addc_u32 s17, s89, 0
	s_add_u32 s18, s88, 0x4900
	s_addc_u32 s19, s89, 0
	s_add_u32 s20, s88, 0x4a00
	s_addc_u32 s21, s89, 0
	s_add_u32 s22, s88, 0x4b00
	s_addc_u32 s23, s89, 0
	s_add_u32 s24, s88, 0x4c00
	s_addc_u32 s25, s89, 0
	s_add_u32 s26, s88, 0x4d00
	s_addc_u32 s27, s89, 0
	s_add_u32 s28, s88, 0x4e00
	s_addc_u32 s29, s89, 0
	s_add_u32 s34, s88, 0x4f00
	s_addc_u32 s35, s89, 0
	s_add_u32 s58, s88, 0x5000
	s_addc_u32 s59, s89, 0
	s_add_u32 s60, s88, 0x5100
	s_addc_u32 s61, s89, 0
	s_add_u32 s74, s88, 0x5200
	s_addc_u32 s75, s89, 0
	s_add_u32 s76, s88, 0x5300
	s_mov_b64 s[36:37], s[86:87]
	s_addc_u32 s77, s89, 0
	s_mov_b32 s31, 1
	v_mov_b32_e32 v17, 0
	s_branch .LBB0_313

; __device__ __forceinline__ unsigned xb_ld(unsigned* p)              { return __hip_atomic_load(p, __ATOMIC_RELAXED, __HIP_MEMORY_SCOPE_AGENT); }
; __device__ __forceinline__ unsigned xb_add(unsigned* p, unsigned v) { return __hip_atomic_fetch_add(p, v, __ATOMIC_RELAXED, __HIP_MEMORY_SCOPE_AGENT); }
; #define XB_SPIN(cond, bar) do { unsigned _sp = 0; while (cond) { __builtin_amdgcn_s_sleep(1); \
;     if ((++_sp & 255u) == 0u) { if (xb_ld(&(bar)[XB_TMO])) break; if (_sp > XB_SPIN_CAP) { atomicAdd(&(bar)[XB_TMO], 1u); break; } } } } while (0)
; __device__ __forceinline__ void xcd_barrier(const XcdBarrier& b) {
;     asm volatile("s_waitcnt vmcnt(0)" ::: "memory");
;     __syncthreads();
;     if (threadIdx.x == 0) {
;         unsigned* bar = b.bar;
;         __builtin_amdgcn_s_waitcnt(0);
;         unsigned nloc = b.st[0], nx = b.st[1];
;         if (nloc == 0u) { xcd_barrier_complete(bar, b.x, nloc, nx); b.st[0] = nloc; b.st[1] = nx; }
;         const unsigned old = xb_add(&bar[XB_XSUB(b.x)], 1u);
;         const unsigned gen = old / nloc;
;         asm volatile("buffer_inv sc1" ::: "memory");
;         if (old + 1u == (gen + 1u) * nloc) {
;             __builtin_amdgcn_fence(__ATOMIC_RELEASE, "agent");
;             asm volatile("s_waitcnt vmcnt(0)" ::: "memory");
;             const unsigned og = xb_add(&bar[XB_TOP], 1u);
;             const unsigned tg = og / nx;
;             if (og + 1u == (tg + 1u) * nx) xb_add(&bar[XB_TOPGEN], 1u);
;             else XB_SPIN(xb_ld(&bar[XB_TOPGEN]) == tg, bar);
;             asm volatile("" ::: "memory");
;             xb_add(&bar[XB_XGEN(b.x)], 1u);
;             asm volatile("s_waitcnt vmcnt(0)" ::: "memory");
;         } else {
;             XB_SPIN(xb_ld(&bar[XB_XGEN(b.x)]) == gen, bar);
;             asm volatile("" ::: "memory");
;             asm volatile("s_waitcnt vmcnt(0)" ::: "memory");
;         }
;     }
;     __syncthreads();
.LBB0_541:
	s_waitcnt vmcnt(0)
	s_barrier
	s_mov_b64 s[2:3], exec
	v_readlane_b32 s4, v241, 34
	v_readlane_b32 s5, v241, 35
	s_and_b64 s[4:5], s[2:3], s[4:5]
	v_readlane_b32 s82, v241, 50
	v_readlane_b32 s83, v241, 51
	s_mov_b64 exec, s[4:5]
	s_cbranch_execz .LBB0_593
	s_bitcmp1_b32 s98, 0
	s_cbranch_scc1 .Lgb_orig3
	s_waitcnt vmcnt(0) lgkmcnt(0)
	s_and_b32 s100, s98, -4
	v_mov_b32_e32 v1, s100
	v_mov_b32_e32 v2, 1
	global_store_dword v1, v2, s[88:89] offset:3072
	buffer_inv sc1
	s_mov_b32 exec_lo, -1
	s_mov_b32 exec_hi, 0
	v_mbcnt_lo_u32_b32 v3, -1, 0
	v_lshl_add_u32 v3, v3, 2, s99
	s_mov_b32 s100, 0

; __device__ __forceinline__ unsigned xb_ld(unsigned* p)              { return __hip_atomic_load(p, __ATOMIC_RELAXED, __HIP_MEMORY_SCOPE_AGENT); }
; __device__ __forceinline__ unsigned xb_add(unsigned* p, unsigned v) { return __hip_atomic_fetch_add(p, v, __ATOMIC_RELAXED, __HIP_MEMORY_SCOPE_AGENT); }
; #define XB_SPIN(cond, bar) do { unsigned _sp = 0; while (cond) { __builtin_amdgcn_s_sleep(1); \
;     if ((++_sp & 255u) == 0u) { if (xb_ld(&(bar)[XB_TMO])) break; if (_sp > XB_SPIN_CAP) { atomicAdd(&(bar)[XB_TMO], 1u); break; } } } } while (0)
; __device__ __forceinline__ void xcd_barrier(const XcdBarrier& b) {
;     asm volatile("s_waitcnt vmcnt(0)" ::: "memory");
;     __syncthreads();
;     if (threadIdx.x == 0) {
;         unsigned* bar = b.bar;
;         __builtin_amdgcn_s_waitcnt(0);
;         unsigned nloc = b.st[0], nx = b.st[1];
;         if (nloc == 0u) { xcd_barrier_complete(bar, b.x, nloc, nx); b.st[0] = nloc; b.st[1] = nx; }
;         const unsigned old = xb_add(&bar[XB_XSUB(b.x)], 1u);
;         const unsigned gen = old / nloc;
;         asm volatile("buffer_inv sc1" ::: "memory");
;         if (old + 1u == (gen + 1u) * nloc) {
;             __builtin_amdgcn_fence(__ATOMIC_RELEASE, "agent");
;             asm volatile("s_waitcnt vmcnt(0)" ::: "memory");
;             const unsigned og = xb_add(&bar[XB_TOP], 1u);
;             const unsigned tg = og / nx;
;             if (og + 1u == (tg + 1u) * nx) xb_add(&bar[XB_TOPGEN], 1u);
;             else XB_SPIN(xb_ld(&bar[XB_TOPGEN]) == tg, bar);
;             asm volatile("" ::: "memory");
;             xb_add(&bar[XB_XGEN(b.x)], 1u);
;             asm volatile("s_waitcnt vmcnt(0)" ::: "memory");
;         } else {
;             XB_SPIN(xb_ld(&bar[XB_XGEN(b.x)]) == gen, bar);
;             asm volatile("" ::: "memory");
;             asm volatile("s_waitcnt vmcnt(0)" ::: "memory");
;         }
;     }
;     __syncthreads();
.LBB0_1103:
	s_waitcnt vmcnt(0)
	s_barrier
	s_mov_b64 s[2:3], exec
	v_readlane_b32 s4, v241, 34
	v_readlane_b32 s5, v241, 35
	s_and_b64 s[4:5], s[2:3], s[4:5]
	s_mov_b64 exec, s[4:5]
	s_cbranch_execz .LBB0_1155
	s_bitcmp1_b32 s98, 0
	s_cbranch_scc1 .Lgb_orig5
	s_waitcnt vmcnt(0) lgkmcnt(0)
	s_and_b32 s100, s98, -4
	s_addk_i32 s100, 0x1000
	v_mov_b32_e32 v1, s100
	v_mov_b32_e32 v2, 1
	global_store_dword v1, v2, s[88:89] offset:1024
	buffer_inv sc1
	s_mov_b32 exec_lo, -1
	s_mov_b32 exec_hi, 0
	v_mbcnt_lo_u32_b32 v3, -1, 0
	v_lshl_add_u32 v3, v3, 2, s99
	v_add_u32_e32 v3, 0x1000, v3
	s_mov_b32 s100, 0

; __device__ __forceinline__ unsigned xb_ld(unsigned* p)              { return __hip_atomic_load(p, __ATOMIC_RELAXED, __HIP_MEMORY_SCOPE_AGENT); }
; __device__ __forceinline__ unsigned xb_add(unsigned* p, unsigned v) { return __hip_atomic_fetch_add(p, v, __ATOMIC_RELAXED, __HIP_MEMORY_SCOPE_AGENT); }
; __device__ __forceinline__ void xcd_barrier_complete(unsigned* bar, unsigned x, unsigned& nloc, unsigned& nx) {
;     const unsigned G = gridDim.x * gridDim.y * gridDim.z;
;     unsigned sum, cnt, mine, sp = 0u;
;     for (;;) {
;         sum = 0u; cnt = 0u; mine = 0u;
; #pragma unroll
;         for (unsigned j = 0; j < 16; ++j) { const unsigned c = xb_ld(&bar[XB_XCNT(j)]); sum += c; cnt += (c > 0u) ? 1u : 0u; mine = (j == x) ? c : mine; }
;         if (sum == G) break;
;         __builtin_amdgcn_s_sleep(1);
;         if ((++sp & 255u) == 0u) { if (xb_ld(&bar[XB_TMO])) break; if (sp > XB_SPIN_CAP) { atomicAdd(&bar[XB_TMO], 1u); break; } }
;     }
;     nloc = mine > 0u ? mine : 1u; nx = cnt > 0u ? cnt : 1u;
; }
; __device__ __forceinline__ void xcd_barrier(const XcdBarrier& b) {
;     asm volatile("s_waitcnt vmcnt(0)" ::: "memory");
;     __syncthreads();
;     if (threadIdx.x == 0) {
;         unsigned* bar = b.bar;
;         __builtin_amdgcn_s_waitcnt(0);
;         unsigned nloc = b.st[0], nx = b.st[1];
;         if (nloc == 0u) { xcd_barrier_complete(bar, b.x, nloc, nx); b.st[0] = nloc; b.st[1] = nx; }
;         const unsigned old = xb_add(&bar[XB_XSUB(b.x)], 1u);
.Lgb_orig5:
	s_add_i32 s4, 0, 0x27f60
	v_mov_b32_e32 v1, s4
	s_waitcnt vmcnt(0) expcnt(0) lgkmcnt(0)
	ds_read_b32 v3, v1
	s_add_i32 s4, 0, 0x27f64
	v_mov_b32_e32 v1, s4
	ds_read_b32 v1, v1
	s_waitcnt lgkmcnt(1)
	v_cmp_ne_u32_e32 vcc, 0, v3
	s_cbranch_vccnz .LBB0_1119
	v_readlane_b32 s4, v241, 0
	v_readlane_b32 s5, v241, 1
	s_load_dwordx2 s[8:9], s[4:5], 0x4
	s_add_u32 s4, s88, 0x4200
	s_addc_u32 s5, s89, 0
	s_add_u32 s6, s88, 0x4400
	s_addc_u32 s7, s89, 0
	s_waitcnt lgkmcnt(0)
	s_mul_i32 s30, s8, s76
	s_add_u32 s8, s88, 0x4500
	s_mul_i32 s30, s30, s9
	s_addc_u32 s9, s89, 0
	s_add_u32 s10, s88, 0x4600
	s_addc_u32 s11, s89, 0
	s_add_u32 s12, s88, 0x4700
	s_addc_u32 s13, s89, 0
	s_add_u32 s14, s88, 0x4800
	s_addc_u32 s15, s89, 0
	s_add_u32 s16, s88, 0x4900
	s_addc_u32 s17, s89, 0
	s_add_u32 s18, s88, 0x4a00
	s_addc_u32 s19, s89, 0
	s_add_u32 s20, s88, 0x4b00
	s_addc_u32 s21, s89, 0
	s_add_u32 s22, s88, 0x4c00
	s_addc_u32 s23, s89, 0
	s_add_u32 s24, s88, 0x4d00
	s_addc_u32 s25, s89, 0
	s_add_u32 s26, s88, 0x4e00
	s_addc_u32 s27, s89, 0
	s_add_u32 s28, s88, 0x4f00
	s_addc_u32 s29, s89, 0
	s_add_u32 s34, s88, 0x5000
	s_addc_u32 s35, s89, 0
	s_add_u32 s36, s88, 0x5100
	s_addc_u32 s37, s89, 0
	s_add_u32 s38, s88, 0x5200
	s_addc_u32 s39, s89, 0
	s_add_u32 s42, s88, 0x5300
	s_addc_u32 s43, s89, 0
	s_mov_b32 s31, 1
	v_mov_b32_e32 v17, 0
	s_branch .LBB0_1107

; __device__ __forceinline__ unsigned xb_ld(unsigned* p)              { return __hip_atomic_load(p, __ATOMIC_RELAXED, __HIP_MEMORY_SCOPE_AGENT); }
; __device__ __forceinline__ unsigned xb_add(unsigned* p, unsigned v) { return __hip_atomic_fetch_add(p, v, __ATOMIC_RELAXED, __HIP_MEMORY_SCOPE_AGENT); }
; #define XB_SPIN(cond, bar) do { unsigned _sp = 0; while (cond) { __builtin_amdgcn_s_sleep(1); \
;     if ((++_sp & 255u) == 0u) { if (xb_ld(&(bar)[XB_TMO])) break; if (_sp > XB_SPIN_CAP) { atomicAdd(&(bar)[XB_TMO], 1u); break; } } } } while (0)
; __device__ __forceinline__ void xcd_barrier(const XcdBarrier& b) {
;     asm volatile("s_waitcnt vmcnt(0)" ::: "memory");
;     __syncthreads();
;     if (threadIdx.x == 0) {
;         unsigned* bar = b.bar;
;         __builtin_amdgcn_s_waitcnt(0);
;         unsigned nloc = b.st[0], nx = b.st[1];
;         if (nloc == 0u) { xcd_barrier_complete(bar, b.x, nloc, nx); b.st[0] = nloc; b.st[1] = nx; }
;         const unsigned old = xb_add(&bar[XB_XSUB(b.x)], 1u);
;         const unsigned gen = old / nloc;
;         asm volatile("buffer_inv sc1" ::: "memory");
;         if (old + 1u == (gen + 1u) * nloc) {
;             __builtin_amdgcn_fence(__ATOMIC_RELEASE, "agent");
;             asm volatile("s_waitcnt vmcnt(0)" ::: "memory");
;             const unsigned og = xb_add(&bar[XB_TOP], 1u);
;             const unsigned tg = og / nx;
;             if (og + 1u == (tg + 1u) * nx) xb_add(&bar[XB_TOPGEN], 1u);
;             else XB_SPIN(xb_ld(&bar[XB_TOPGEN]) == tg, bar);
;             asm volatile("" ::: "memory");
;             xb_add(&bar[XB_XGEN(b.x)], 1u);
;             asm volatile("s_waitcnt vmcnt(0)" ::: "memory");
;         } else {
;             XB_SPIN(xb_ld(&bar[XB_XGEN(b.x)]) == gen, bar);
;             asm volatile("" ::: "memory");
;             asm volatile("s_waitcnt vmcnt(0)" ::: "memory");
;         }
;     }
;     __syncthreads();
.LBB0_1242:
	s_waitcnt vmcnt(0)
	s_waitcnt lgkmcnt(0)
	s_barrier
	s_mov_b64 s[0:1], exec
	v_readlane_b32 s6, v241, 34
	v_readlane_b32 s7, v241, 35
	v_readlane_b32 s78, v241, 55
	s_and_b64 s[6:7], s[0:1], s[6:7]
	v_readlane_b32 s79, v241, 56
	s_mov_b64 exec, s[6:7]
	s_cbranch_execz .LBB0_1294
	s_bitcmp1_b32 s98, 0
	s_cbranch_scc1 .Lgb_orig6
	s_waitcnt vmcnt(0) lgkmcnt(0)
	s_and_b32 s100, s98, -4
	s_addk_i32 s100, 0x1000
	v_mov_b32_e32 v1, s100
	v_mov_b32_e32 v2, 1
	global_store_dword v1, v2, s[88:89] offset:2048
	buffer_inv sc1
	s_mov_b32 exec_lo, -1
	s_mov_b32 exec_hi, 0
	v_mbcnt_lo_u32_b32 v3, -1, 0
	v_lshl_add_u32 v3, v3, 2, s99
	v_add_u32_e32 v3, 0x1000, v3
	s_mov_b32 s100, 0

; __device__ __forceinline__ unsigned xb_ld(unsigned* p)              { return __hip_atomic_load(p, __ATOMIC_RELAXED, __HIP_MEMORY_SCOPE_AGENT); }
; __device__ __forceinline__ unsigned xb_add(unsigned* p, unsigned v) { return __hip_atomic_fetch_add(p, v, __ATOMIC_RELAXED, __HIP_MEMORY_SCOPE_AGENT); }
; __device__ __forceinline__ void xcd_barrier_complete(unsigned* bar, unsigned x, unsigned& nloc, unsigned& nx) {
;     const unsigned G = gridDim.x * gridDim.y * gridDim.z;
;     unsigned sum, cnt, mine, sp = 0u;
;     for (;;) {
;         sum = 0u; cnt = 0u; mine = 0u;
; #pragma unroll
;         for (unsigned j = 0; j < 16; ++j) { const unsigned c = xb_ld(&bar[XB_XCNT(j)]); sum += c; cnt += (c > 0u) ? 1u : 0u; mine = (j == x) ? c : mine; }
;         if (sum == G) break;
;         __builtin_amdgcn_s_sleep(1);
;         if ((++sp & 255u) == 0u) { if (xb_ld(&bar[XB_TMO])) break; if (sp > XB_SPIN_CAP) { atomicAdd(&bar[XB_TMO], 1u); break; } }
;     }
;     nloc = mine > 0u ? mine : 1u; nx = cnt > 0u ? cnt : 1u;
; }
; __device__ __forceinline__ void xcd_barrier(const XcdBarrier& b) {
;     asm volatile("s_waitcnt vmcnt(0)" ::: "memory");
;     __syncthreads();
;     if (threadIdx.x == 0) {
;         unsigned* bar = b.bar;
;         __builtin_amdgcn_s_waitcnt(0);
;         unsigned nloc = b.st[0], nx = b.st[1];
;         if (nloc == 0u) { xcd_barrier_complete(bar, b.x, nloc, nx); b.st[0] = nloc; b.st[1] = nx; }
;         const unsigned old = xb_add(&bar[XB_XSUB(b.x)], 1u);
.Lgb_orig6:
	s_add_i32 s6, 0, 0x27f60
	v_mov_b32_e32 v1, s6
	s_waitcnt vmcnt(0) expcnt(0) lgkmcnt(0)
	ds_read_b32 v3, v1
	s_add_i32 s6, 0, 0x27f64
	v_mov_b32_e32 v1, s6
	ds_read_b32 v1, v1
	s_waitcnt lgkmcnt(1)
	v_cmp_ne_u32_e32 vcc, 0, v3
	s_cbranch_vccnz .LBB0_1258
	v_readlane_b32 s6, v241, 0
	v_readlane_b32 s7, v241, 1
	s_load_dwordx2 s[10:11], s[6:7], 0x4
	s_add_u32 s6, s88, 0x4200
	s_addc_u32 s7, s89, 0
	s_add_u32 s8, s88, 0x4400
	s_addc_u32 s9, s89, 0
	s_waitcnt lgkmcnt(0)
	s_mul_i32 s30, s10, s76
	s_add_u32 s10, s88, 0x4500
	s_mul_i32 s30, s30, s11
	s_addc_u32 s11, s89, 0
	s_add_u32 s14, s88, 0x4600
	s_addc_u32 s15, s89, 0
	s_add_u32 s16, s88, 0x4700
	s_addc_u32 s17, s89, 0
	s_add_u32 s18, s88, 0x4800
	s_addc_u32 s19, s89, 0
	s_add_u32 s20, s88, 0x4900
	s_addc_u32 s21, s89, 0
	s_add_u32 s22, s88, 0x4a00
	s_addc_u32 s23, s89, 0
	s_add_u32 s24, s88, 0x4b00
	s_addc_u32 s25, s89, 0
	s_add_u32 s26, s88, 0x4c00
	s_addc_u32 s27, s89, 0
	s_add_u32 s28, s88, 0x4d00
	s_addc_u32 s29, s89, 0
	s_add_u32 s34, s88, 0x4e00
	s_addc_u32 s35, s89, 0
	s_add_u32 s36, s88, 0x4f00
	s_addc_u32 s37, s89, 0
	s_add_u32 s38, s88, 0x5000
	s_addc_u32 s39, s89, 0
	s_add_u32 s40, s88, 0x5100
	s_addc_u32 s41, s89, 0
	s_add_u32 s42, s88, 0x5200
	s_addc_u32 s43, s89, 0
	s_add_u32 s44, s88, 0x5300
	s_addc_u32 s45, s89, 0
	s_mov_b32 s31, 1
	v_mov_b32_e32 v17, 0
	s_branch .LBB0_1246

; __device__ __forceinline__ unsigned xb_ld(unsigned* p)              { return __hip_atomic_load(p, __ATOMIC_RELAXED, __HIP_MEMORY_SCOPE_AGENT); }
; __device__ __forceinline__ unsigned xb_add(unsigned* p, unsigned v) { return __hip_atomic_fetch_add(p, v, __ATOMIC_RELAXED, __HIP_MEMORY_SCOPE_AGENT); }
; #define XB_SPIN(cond, bar) do { unsigned _sp = 0; while (cond) { __builtin_amdgcn_s_sleep(1); \
;     if ((++_sp & 255u) == 0u) { if (xb_ld(&(bar)[XB_TMO])) break; if (_sp > XB_SPIN_CAP) { atomicAdd(&(bar)[XB_TMO], 1u); break; } } } } while (0)
; __device__ __forceinline__ void xcd_barrier(const XcdBarrier& b) {
;     asm volatile("s_waitcnt vmcnt(0)" ::: "memory");
;     __syncthreads();
;     if (threadIdx.x == 0) {
;         unsigned* bar = b.bar;
;         __builtin_amdgcn_s_waitcnt(0);
;         unsigned nloc = b.st[0], nx = b.st[1];
;         if (nloc == 0u) { xcd_barrier_complete(bar, b.x, nloc, nx); b.st[0] = nloc; b.st[1] = nx; }
;         const unsigned old = xb_add(&bar[XB_XSUB(b.x)], 1u);
;         const unsigned gen = old / nloc;
;         asm volatile("buffer_inv sc1" ::: "memory");
;         if (old + 1u == (gen + 1u) * nloc) {
;             __builtin_amdgcn_fence(__ATOMIC_RELEASE, "agent");
;             asm volatile("s_waitcnt vmcnt(0)" ::: "memory");
;             const unsigned og = xb_add(&bar[XB_TOP], 1u);
;             const unsigned tg = og / nx;
;             if (og + 1u == (tg + 1u) * nx) xb_add(&bar[XB_TOPGEN], 1u);
;             else XB_SPIN(xb_ld(&bar[XB_TOPGEN]) == tg, bar);
;             asm volatile("" ::: "memory");
;             xb_add(&bar[XB_XGEN(b.x)], 1u);
;             asm volatile("s_waitcnt vmcnt(0)" ::: "memory");
;         } else {
;             XB_SPIN(xb_ld(&bar[XB_XGEN(b.x)]) == gen, bar);
;             asm volatile("" ::: "memory");
;             asm volatile("s_waitcnt vmcnt(0)" ::: "memory");
;         }
;     }
;     __syncthreads();
.LBB0_1352:
	s_waitcnt vmcnt(0)
	s_waitcnt vmcnt(0)
	s_barrier
	s_mov_b64 s[0:1], exec
	v_readlane_b32 s6, v241, 34
	v_readlane_b32 s7, v241, 35
	s_and_b64 s[6:7], s[0:1], s[6:7]
	s_mov_b64 exec, s[6:7]
	s_cbranch_execz .LBB0_1404
	s_bitcmp1_b32 s98, 0
	s_cbranch_scc1 .Lgb_orig7
	s_waitcnt vmcnt(0) lgkmcnt(0)
	s_and_b32 s100, s98, -4
	s_addk_i32 s100, 0x1000
	v_mov_b32_e32 v1, s100
	v_mov_b32_e32 v2, 1
	global_store_dword v1, v2, s[88:89] offset:3072
	buffer_inv sc1
	s_mov_b32 exec_lo, -1
	s_mov_b32 exec_hi, 0
	v_mbcnt_lo_u32_b32 v3, -1, 0
	v_lshl_add_u32 v3, v3, 2, s99
	v_add_u32_e32 v3, 0x1000, v3
	s_mov_b32 s100, 0
